# v102 + one s_nop in the GEMM K-loop's 4th load segment so that all eight MFMA bursts start at address phase 4 mod 8 (and one after the loop to keep later code in place)
# speedup vs baseline: 1.0003x; 1.0003x over previous
.LBB0_173:
	s_add_i32 s92, s90, 2
	s_add_u32 s93, s16, 0x80
	s_addc_u32 s91, s17, 0
	s_add_i32 s8, 0, 0x10000
	s_cmp_eq_u32 s35, s90
	s_cselect_b32 s91, s47, s91
	s_cselect_b32 s90, s46, s93
	s_cselect_b32 vcc_hi, s87, s89
	s_cselect_b32 vcc_lo, s86, s14
	s_add_i32 s9, 0, 0x14000
	v_add_u32_e32 v142, s8, v195
	v_add_u32_e32 v172, s9, v195
	s_waitcnt lgkmcnt(0)
	ds_read_b128 v[130:133], v142
	ds_read_b128 v[134:137], v142 offset:1024
	ds_read_b128 v[138:141], v142 offset:2048
	ds_read_b128 v[142:145], v142 offset:3072
	ds_read_b128 v[146:149], v172
	ds_read_b128 v[150:153], v172 offset:1024
	ds_read_b128 v[154:157], v172 offset:2048
	ds_read_b128 v[172:175], v172 offset:3072
	v_lshl_add_u64 v[236:237], s[16:17], 0, v[168:169]
	s_add_i32 m0, s97, 0xc000
	ds_read_b128 v[176:179], v208
	ds_read_b128 v[180:183], v208 offset:1024
	ds_read_b128 v[212:215], v208 offset:2048
	ds_read_b128 v[216:219], v208 offset:3072
	ds_read_b128 v[220:223], v208 offset:4096
	ds_read_b128 v[224:227], v208 offset:5120
	ds_read_b128 v[228:231], v208 offset:6144
	ds_read_b128 v[232:235], v208 offset:7168
	global_load_lds_dwordx4 v[236:237], off
	v_lshl_add_u64 v[236:237], s[16:17], 0, v[170:171]
	s_add_i32 m0, s97, 0xe000
	s_nop 0
	global_load_lds_dwordx4 v[236:237], off
	s_waitcnt vmcnt(8)
	s_waitcnt lgkmcnt(0)
	s_barrier
	s_setprio 1
	s_waitcnt lgkmcnt(0)
	v_mfma_f32_16x16x32_bf16 v[126:129], v[130:133], v[176:179], v[126:129]
	v_mfma_f32_16x16x32_bf16 v[122:125], v[138:141], v[176:179], v[122:125]
	v_mfma_f32_16x16x32_bf16 v[114:117], v[130:133], v[212:215], v[114:117]
	v_mfma_f32_16x16x32_bf16 v[106:109], v[138:141], v[212:215], v[106:109]
	v_mfma_f32_16x16x32_bf16 v[98:101], v[130:133], v[220:223], v[98:101]
	v_mfma_f32_16x16x32_bf16 v[90:93], v[138:141], v[220:223], v[90:93]
	v_mfma_f32_16x16x32_bf16 v[82:85], v[130:133], v[228:231], v[82:85]
	v_mfma_f32_16x16x32_bf16 v[74:77], v[138:141], v[228:231], v[74:77]
	v_mfma_f32_16x16x32_bf16 v[126:129], v[134:137], v[180:183], v[126:129]
	v_mfma_f32_16x16x32_bf16 v[122:125], v[142:145], v[180:183], v[122:125]
	v_mfma_f32_16x16x32_bf16 v[114:117], v[134:137], v[216:219], v[114:117]
	v_mfma_f32_16x16x32_bf16 v[106:109], v[142:145], v[216:219], v[106:109]
	v_mfma_f32_16x16x32_bf16 v[98:101], v[134:137], v[224:227], v[98:101]
	v_mfma_f32_16x16x32_bf16 v[90:93], v[142:145], v[224:227], v[90:93]
	v_mfma_f32_16x16x32_bf16 v[82:85], v[134:137], v[232:235], v[82:85]
	v_mfma_f32_16x16x32_bf16 v[74:77], v[142:145], v[232:235], v[74:77]
	s_setprio 0
	s_setprio 1
	v_mfma_f32_16x16x32_bf16 v[118:121], v[146:149], v[176:179], v[118:121]
	v_mfma_f32_16x16x32_bf16 v[110:113], v[154:157], v[176:179], v[110:113]
	v_mfma_f32_16x16x32_bf16 v[102:105], v[146:149], v[212:215], v[102:105]
	v_mfma_f32_16x16x32_bf16 v[94:97], v[154:157], v[212:215], v[94:97]
	v_mfma_f32_16x16x32_bf16 v[86:89], v[146:149], v[220:223], v[86:89]
	v_mfma_f32_16x16x32_bf16 v[78:81], v[154:157], v[220:223], v[78:81]
	v_mfma_f32_16x16x32_bf16 v[70:73], v[146:149], v[228:231], v[70:73]
	v_mfma_f32_16x16x32_bf16 v[66:69], v[154:157], v[228:231], v[66:69]
	v_mfma_f32_16x16x32_bf16 v[118:121], v[150:153], v[180:183], v[118:121]
	v_mfma_f32_16x16x32_bf16 v[110:113], v[172:175], v[180:183], v[110:113]
	v_mfma_f32_16x16x32_bf16 v[102:105], v[150:153], v[216:219], v[102:105]
	v_mfma_f32_16x16x32_bf16 v[94:97], v[172:175], v[216:219], v[94:97]
	v_mfma_f32_16x16x32_bf16 v[86:89], v[150:153], v[224:227], v[86:89]
	v_mfma_f32_16x16x32_bf16 v[78:81], v[172:175], v[224:227], v[78:81]
	v_mfma_f32_16x16x32_bf16 v[70:73], v[150:153], v[232:235], v[70:73]
	v_mfma_f32_16x16x32_bf16 v[66:69], v[172:175], v[232:235], v[66:69]
	s_setprio 0
	s_barrier
	s_add_i32 s8, s8, s96
	v_lshl_add_u64 v[236:237], vcc, 0, v[0:1]
	s_mov_b32 m0, s8
	ds_read_b128 v[176:179], v208 offset:16384
	ds_read_b128 v[180:183], v208 offset:17408
	ds_read_b128 v[212:215], v208 offset:18432
	ds_read_b128 v[216:219], v208 offset:19456
	ds_read_b128 v[220:223], v208 offset:20480
	ds_read_b128 v[224:227], v208 offset:21504
	ds_read_b128 v[228:231], v208 offset:22528
	ds_read_b128 v[232:235], v208 offset:23552
	global_load_lds_dwordx4 v[236:237], off
	s_add_i32 m0, s8, 0x2000
	v_lshl_add_u64 v[238:239], vcc, 0, v[162:163]
	s_add_u32 vcc_lo, vcc_lo, s74
	s_addc_u32 vcc_hi, vcc_hi, s75
	s_add_i32 s8, s9, s96
	global_load_lds_dwordx4 v[238:239], off
	v_lshl_add_u64 v[240:241], vcc, 0, v[0:1]
	s_mov_b32 m0, s8
	v_lshl_add_u64 v[242:243], vcc, 0, v[162:163]
	global_load_lds_dwordx4 v[240:241], off
	s_add_i32 m0, s8, 0x2000
	v_lshl_add_u64 v[244:245], s[90:91], 0, v[158:159]
	global_load_lds_dwordx4 v[242:243], off
	s_mov_b32 m0, s97
	v_lshl_add_u64 v[246:247], s[90:91], 0, v[160:161]
	global_load_lds_dwordx4 v[244:245], off
	s_mov_b32 m0, s98
	s_nop 0
	global_load_lds_dwordx4 v[246:247], off
	s_waitcnt vmcnt(8)
	s_waitcnt lgkmcnt(0)
	s_barrier
	s_setprio 1
	s_waitcnt lgkmcnt(0)
	v_mfma_f32_16x16x32_bf16 v[62:65], v[130:133], v[176:179], v[62:65]
	v_mfma_f32_16x16x32_bf16 v[58:61], v[138:141], v[176:179], v[58:61]
	v_mfma_f32_16x16x32_bf16 v[50:53], v[130:133], v[212:215], v[50:53]
	v_mfma_f32_16x16x32_bf16 v[42:45], v[138:141], v[212:215], v[42:45]
	v_mfma_f32_16x16x32_bf16 v[34:37], v[130:133], v[220:223], v[34:37]
	v_mfma_f32_16x16x32_bf16 v[26:29], v[138:141], v[220:223], v[26:29]
	v_mfma_f32_16x16x32_bf16 v[18:21], v[130:133], v[228:231], v[18:21]
	v_mfma_f32_16x16x32_bf16 v[10:13], v[138:141], v[228:231], v[10:13]
	v_mfma_f32_16x16x32_bf16 v[62:65], v[134:137], v[180:183], v[62:65]
	v_mfma_f32_16x16x32_bf16 v[58:61], v[142:145], v[180:183], v[58:61]
	v_mfma_f32_16x16x32_bf16 v[50:53], v[134:137], v[216:219], v[50:53]
	v_mfma_f32_16x16x32_bf16 v[42:45], v[142:145], v[216:219], v[42:45]
	v_mfma_f32_16x16x32_bf16 v[34:37], v[134:137], v[224:227], v[34:37]
	v_mfma_f32_16x16x32_bf16 v[26:29], v[142:145], v[224:227], v[26:29]
	v_mfma_f32_16x16x32_bf16 v[18:21], v[134:137], v[232:235], v[18:21]
	v_mfma_f32_16x16x32_bf16 v[10:13], v[142:145], v[232:235], v[10:13]
	s_setprio 0
	s_setprio 1
	v_mfma_f32_16x16x32_bf16 v[54:57], v[146:149], v[176:179], v[54:57]
	v_mfma_f32_16x16x32_bf16 v[46:49], v[154:157], v[176:179], v[46:49]
	v_mfma_f32_16x16x32_bf16 v[38:41], v[146:149], v[212:215], v[38:41]
	v_mfma_f32_16x16x32_bf16 v[30:33], v[154:157], v[212:215], v[30:33]
	v_mfma_f32_16x16x32_bf16 v[22:25], v[146:149], v[220:223], v[22:25]
	v_mfma_f32_16x16x32_bf16 v[14:17], v[154:157], v[220:223], v[14:17]
	v_mfma_f32_16x16x32_bf16 v[6:9], v[146:149], v[228:231], v[6:9]
	v_mfma_f32_16x16x32_bf16 v[2:5], v[154:157], v[228:231], v[2:5]
	v_mfma_f32_16x16x32_bf16 v[54:57], v[150:153], v[180:183], v[54:57]
	v_mfma_f32_16x16x32_bf16 v[46:49], v[172:175], v[180:183], v[46:49]
	v_mfma_f32_16x16x32_bf16 v[38:41], v[150:153], v[216:219], v[38:41]
	v_mfma_f32_16x16x32_bf16 v[30:33], v[172:175], v[216:219], v[30:33]
	v_mfma_f32_16x16x32_bf16 v[22:25], v[150:153], v[224:227], v[22:25]
	v_mfma_f32_16x16x32_bf16 v[14:17], v[172:175], v[224:227], v[14:17]
	v_mfma_f32_16x16x32_bf16 v[6:9], v[150:153], v[232:235], v[6:9]
	v_mfma_f32_16x16x32_bf16 v[2:5], v[172:175], v[232:235], v[2:5]
	s_setprio 0
	s_barrier
	s_add_i32 s8, 0, 0x18000
	s_add_i32 s9, 0, 0x1c000
	v_add_u32_e32 v142, s8, v195
	v_add_u32_e32 v172, s9, v195
	ds_read_b128 v[130:133], v142
	ds_read_b128 v[134:137], v142 offset:1024
	ds_read_b128 v[138:141], v142 offset:2048
	ds_read_b128 v[142:145], v142 offset:3072
	ds_read_b128 v[146:149], v172
	ds_read_b128 v[150:153], v172 offset:1024
	ds_read_b128 v[154:157], v172 offset:2048
	ds_read_b128 v[172:175], v172 offset:3072
	s_add_u32 s90, s90, s72
	s_addc_u32 s91, s91, s73
	s_mov_b32 m0, s99
	v_lshl_add_u64 v[248:249], s[90:91], 0, v[158:159]
	ds_read_b128 v[176:179], v208 offset:32768
	ds_read_b128 v[180:183], v208 offset:33792
	ds_read_b128 v[212:215], v208 offset:34816
	ds_read_b128 v[216:219], v208 offset:35840
	ds_read_b128 v[220:223], v208 offset:36864
	ds_read_b128 v[224:227], v208 offset:37888
	ds_read_b128 v[228:231], v208 offset:38912
	ds_read_b128 v[232:235], v208 offset:39936
	global_load_lds_dwordx4 v[248:249], off
	v_lshl_add_u64 v[248:249], s[90:91], 0, v[160:161]
	s_mov_b32 m0, s48
	s_nop 0
	global_load_lds_dwordx4 v[248:249], off
	s_waitcnt vmcnt(8)
	s_waitcnt lgkmcnt(0)
	s_barrier
	s_setprio 1
	s_waitcnt lgkmcnt(0)
	v_mfma_f32_16x16x32_bf16 v[126:129], v[130:133], v[176:179], v[126:129]
	v_mfma_f32_16x16x32_bf16 v[122:125], v[138:141], v[176:179], v[122:125]
	v_mfma_f32_16x16x32_bf16 v[114:117], v[130:133], v[212:215], v[114:117]
	v_mfma_f32_16x16x32_bf16 v[106:109], v[138:141], v[212:215], v[106:109]
	v_mfma_f32_16x16x32_bf16 v[98:101], v[130:133], v[220:223], v[98:101]
	v_mfma_f32_16x16x32_bf16 v[90:93], v[138:141], v[220:223], v[90:93]
	v_mfma_f32_16x16x32_bf16 v[82:85], v[130:133], v[228:231], v[82:85]
	v_mfma_f32_16x16x32_bf16 v[74:77], v[138:141], v[228:231], v[74:77]
	v_mfma_f32_16x16x32_bf16 v[126:129], v[134:137], v[180:183], v[126:129]
	v_mfma_f32_16x16x32_bf16 v[122:125], v[142:145], v[180:183], v[122:125]
	v_mfma_f32_16x16x32_bf16 v[114:117], v[134:137], v[216:219], v[114:117]
	v_mfma_f32_16x16x32_bf16 v[106:109], v[142:145], v[216:219], v[106:109]
	v_mfma_f32_16x16x32_bf16 v[98:101], v[134:137], v[224:227], v[98:101]
	v_mfma_f32_16x16x32_bf16 v[90:93], v[142:145], v[224:227], v[90:93]
	v_mfma_f32_16x16x32_bf16 v[82:85], v[134:137], v[232:235], v[82:85]
	v_mfma_f32_16x16x32_bf16 v[74:77], v[142:145], v[232:235], v[74:77]
	s_setprio 0
	s_setprio 1
	v_mfma_f32_16x16x32_bf16 v[118:121], v[146:149], v[176:179], v[118:121]
	v_mfma_f32_16x16x32_bf16 v[110:113], v[154:157], v[176:179], v[110:113]
	v_mfma_f32_16x16x32_bf16 v[102:105], v[146:149], v[212:215], v[102:105]
	v_mfma_f32_16x16x32_bf16 v[94:97], v[154:157], v[212:215], v[94:97]
	v_mfma_f32_16x16x32_bf16 v[86:89], v[146:149], v[220:223], v[86:89]
	v_mfma_f32_16x16x32_bf16 v[78:81], v[154:157], v[220:223], v[78:81]
	v_mfma_f32_16x16x32_bf16 v[70:73], v[146:149], v[228:231], v[70:73]
	v_mfma_f32_16x16x32_bf16 v[66:69], v[154:157], v[228:231], v[66:69]
	v_mfma_f32_16x16x32_bf16 v[118:121], v[150:153], v[180:183], v[118:121]
	v_mfma_f32_16x16x32_bf16 v[110:113], v[172:175], v[180:183], v[110:113]
	v_mfma_f32_16x16x32_bf16 v[102:105], v[150:153], v[216:219], v[102:105]
	v_mfma_f32_16x16x32_bf16 v[94:97], v[172:175], v[216:219], v[94:97]
	v_mfma_f32_16x16x32_bf16 v[86:89], v[150:153], v[224:227], v[86:89]
	v_mfma_f32_16x16x32_bf16 v[78:81], v[172:175], v[224:227], v[78:81]
	v_mfma_f32_16x16x32_bf16 v[70:73], v[150:153], v[232:235], v[70:73]
	v_mfma_f32_16x16x32_bf16 v[66:69], v[172:175], v[232:235], v[66:69]
	s_setprio 0
	s_barrier
	s_add_i32 s8, s8, s96
	v_lshl_add_u64 v[236:237], v[236:237], 0, s[18:19]
	s_mov_b32 m0, s8
	ds_read_b128 v[176:179], v208 offset:49152
	ds_read_b128 v[180:183], v208 offset:50176
	ds_read_b128 v[212:215], v208 offset:51200
	ds_read_b128 v[216:219], v208 offset:52224
	ds_read_b128 v[220:223], v208 offset:53248
	ds_read_b128 v[224:227], v208 offset:54272
	ds_read_b128 v[228:231], v208 offset:55296
	ds_read_b128 v[232:235], v208 offset:56320
	global_load_lds_dwordx4 v[236:237], off
	v_lshl_add_u64 v[236:237], v[238:239], 0, s[18:19]
	s_add_i32 m0, s8, 0x2000
	s_add_i32 s8, s9, s96
	global_load_lds_dwordx4 v[236:237], off
	v_lshl_add_u64 v[236:237], v[240:241], 0, s[18:19]
	s_mov_b32 m0, s8
	s_nop 0
	global_load_lds_dwordx4 v[236:237], off
	v_lshl_add_u64 v[236:237], v[242:243], 0, s[18:19]
	s_add_i32 m0, s8, 0x2000
	s_nop 0
	global_load_lds_dwordx4 v[236:237], off
	v_lshl_add_u64 v[236:237], v[244:245], 0, s[18:19]
	s_mov_b32 m0, s31
	s_nop 0
	global_load_lds_dwordx4 v[236:237], off
	v_lshl_add_u64 v[236:237], v[246:247], 0, s[18:19]
	s_mov_b32 m0, s34
	s_nop 0
	global_load_lds_dwordx4 v[236:237], off
	s_waitcnt vmcnt(8)
	s_waitcnt lgkmcnt(0)
	s_nop 0
	s_barrier
	s_setprio 1
	s_waitcnt lgkmcnt(0)
	v_mfma_f32_16x16x32_bf16 v[62:65], v[130:133], v[176:179], v[62:65]
	v_mfma_f32_16x16x32_bf16 v[58:61], v[138:141], v[176:179], v[58:61]
	v_mfma_f32_16x16x32_bf16 v[50:53], v[130:133], v[212:215], v[50:53]
	v_mfma_f32_16x16x32_bf16 v[42:45], v[138:141], v[212:215], v[42:45]
	v_mfma_f32_16x16x32_bf16 v[34:37], v[130:133], v[220:223], v[34:37]
	v_mfma_f32_16x16x32_bf16 v[26:29], v[138:141], v[220:223], v[26:29]
	v_mfma_f32_16x16x32_bf16 v[18:21], v[130:133], v[228:231], v[18:21]
	v_mfma_f32_16x16x32_bf16 v[10:13], v[138:141], v[228:231], v[10:13]
	v_mfma_f32_16x16x32_bf16 v[62:65], v[134:137], v[180:183], v[62:65]
	v_mfma_f32_16x16x32_bf16 v[58:61], v[142:145], v[180:183], v[58:61]
	v_mfma_f32_16x16x32_bf16 v[50:53], v[134:137], v[216:219], v[50:53]
	v_mfma_f32_16x16x32_bf16 v[42:45], v[142:145], v[216:219], v[42:45]
	v_mfma_f32_16x16x32_bf16 v[34:37], v[134:137], v[224:227], v[34:37]
	v_mfma_f32_16x16x32_bf16 v[26:29], v[142:145], v[224:227], v[26:29]
	v_mfma_f32_16x16x32_bf16 v[18:21], v[134:137], v[232:235], v[18:21]
	v_mfma_f32_16x16x32_bf16 v[10:13], v[142:145], v[232:235], v[10:13]
	s_setprio 0
	s_setprio 1
	v_mfma_f32_16x16x32_bf16 v[54:57], v[146:149], v[176:179], v[54:57]
	v_mfma_f32_16x16x32_bf16 v[46:49], v[154:157], v[176:179], v[46:49]
	v_mfma_f32_16x16x32_bf16 v[38:41], v[146:149], v[212:215], v[38:41]
	v_mfma_f32_16x16x32_bf16 v[30:33], v[154:157], v[212:215], v[30:33]
	v_mfma_f32_16x16x32_bf16 v[22:25], v[146:149], v[220:223], v[22:25]
	v_mfma_f32_16x16x32_bf16 v[14:17], v[154:157], v[220:223], v[14:17]
	v_mfma_f32_16x16x32_bf16 v[6:9], v[146:149], v[228:231], v[6:9]
	v_mfma_f32_16x16x32_bf16 v[2:5], v[154:157], v[228:231], v[2:5]
	v_mfma_f32_16x16x32_bf16 v[54:57], v[150:153], v[180:183], v[54:57]
	v_mfma_f32_16x16x32_bf16 v[46:49], v[172:175], v[180:183], v[46:49]
	v_mfma_f32_16x16x32_bf16 v[38:41], v[150:153], v[216:219], v[38:41]
	v_mfma_f32_16x16x32_bf16 v[30:33], v[172:175], v[216:219], v[30:33]
	v_mfma_f32_16x16x32_bf16 v[22:25], v[150:153], v[224:227], v[22:25]
	v_mfma_f32_16x16x32_bf16 v[14:17], v[172:175], v[224:227], v[14:17]
	v_mfma_f32_16x16x32_bf16 v[6:9], v[150:153], v[232:235], v[6:9]
	v_mfma_f32_16x16x32_bf16 v[2:5], v[172:175], v[232:235], v[2:5]
	s_setprio 0
	s_barrier
	s_add_u32 s16, s16, 0x100
	s_addc_u32 s17, s17, 0
	s_add_u32 s14, s14, 0x100
	s_addc_u32 s89, s89, 0
	s_cmp_ge_u32 s92, s30
	s_mov_b32 s90, s92
	s_cbranch_scc0 .LBB0_173
	s_nop 0
	s_and_b64 vcc, exec, s[82:83]
	s_cbranch_vccnz .LBB0_177
	s_andn2_b64 vcc, exec, s[78:79]
	s_mov_b64 s[16:17], -1
	s_cbranch_vccz .LBB0_178
